# N=1p2 handoff + every workgroup issues buffer_wbl2 on arrival at each seam
# baseline (speedup 1.0000x reference)
; __device__ __forceinline__ unsigned xb_ld(unsigned* p)              { return __hip_atomic_load(p, __ATOMIC_RELAXED, __HIP_MEMORY_SCOPE_AGENT); }
; __device__ __forceinline__ void xcd_barrier_complete(unsigned* bar, unsigned x, unsigned& nloc, unsigned& nx) {
;     const unsigned G = gridDim.x * gridDim.y * gridDim.z;
;     unsigned sum, cnt, mine, sp = 0u;
;     for (;;) {
;         sum = 0u; cnt = 0u; mine = 0u;
; #pragma unroll
;         for (unsigned j = 0; j < 16; ++j) { const unsigned c = xb_ld(&bar[XB_XCNT(j)]); sum += c; cnt += (c > 0u) ? 1u : 0u; mine = (j == x) ? c : mine; }
; __device__ __forceinline__ void xcd_barrier(const XcdBarrier& b) {
;     asm volatile("s_waitcnt vmcnt(0)" ::: "memory");
;     __syncthreads();
;     if (threadIdx.x == 0) {
;         unsigned* bar = b.bar;
;         __builtin_amdgcn_s_waitcnt(0);
;         unsigned nloc = b.st[0], nx = b.st[1];
;         if (nloc == 0u) { xcd_barrier_complete(bar, b.x, nloc, nx); b.st[0] = nloc; b.st[1] = nx; }
.LBB0_79:
	s_cmp_gt_i32 s31, 1
	s_cselect_b64 s[0:1], -1, 0
	s_and_b64 s[6:7], s[6:7], s[0:1]
	s_andn2_b64 vcc, exec, s[6:7]
	s_cbranch_vccnz .LBB0_130
	s_waitcnt vmcnt(0)
	v_cmp_eq_u32_e32 vcc, 0, v0
	s_barrier
	s_and_saveexec_b64 s[6:7], vcc
	s_cbranch_execz .LBB0_129
	v_mov_b32_e32 v1, s97
	buffer_wbl2 sc1
	s_waitcnt vmcnt(0) expcnt(0) lgkmcnt(0)
	ds_read_b32 v3, v1
	ds_read_b32 v1, v1 offset:4
	s_waitcnt lgkmcnt(1)
	v_cmp_ne_u32_e32 vcc, 0, v3
	s_cbranch_vccnz .LBB0_97
	v_readlane_b32 s10, v244, 0
	v_readlane_b32 s11, v244, 1
	s_load_dwordx2 s[14:15], s[10:11], 0x4
	s_add_u32 s10, s28, 0x4200
	s_addc_u32 s11, s29, 0
	s_add_u32 s12, s28, 0x4400
	s_addc_u32 s13, s29, 0
	s_waitcnt lgkmcnt(0)
	s_mul_i32 s3, s14, s33
	s_add_u32 s14, s28, 0x4500
	s_mul_i32 s3, s3, s15
	s_addc_u32 s15, s29, 0
	s_add_u32 s16, s28, 0x4600
	s_addc_u32 s17, s29, 0
	s_add_u32 s20, s28, 0x4700
	s_addc_u32 s21, s29, 0
	s_add_u32 s62, s28, 0x4800
	s_addc_u32 s63, s29, 0
	s_add_u32 s66, s28, 0x4900
	s_addc_u32 s67, s29, 0
	s_add_u32 s72, s28, 0x4a00
	s_addc_u32 s73, s29, 0
	s_add_u32 s76, s28, 0x4b00
	s_addc_u32 s77, s29, 0
	s_add_u32 s82, s28, 0x4c00
	s_addc_u32 s83, s29, 0
	s_add_u32 s84, s28, 0x4d00
	s_addc_u32 s85, s29, 0
	s_add_u32 s86, s28, 0x4e00
	s_addc_u32 s87, s29, 0
	s_add_u32 s88, s28, 0x4f00
	s_addc_u32 s89, s29, 0
	s_add_u32 s90, s28, 0x5000
	s_addc_u32 s91, s29, 0
	s_add_u32 s92, s28, 0x5100
	s_mov_b32 s53, s93
	s_addc_u32 s93, s29, 0
	s_add_u32 s94, s28, 0x5200
	s_addc_u32 s95, s29, 0
	s_add_u32 s60, s28, 0x5300
	s_mov_b32 s55, s97
	s_mov_b32 s54, s96
	s_addc_u32 s61, s29, 0
	s_mov_b32 s35, 1
	v_mov_b32_e32 v17, 0
	s_branch .LBB0_84

; __device__ __forceinline__ unsigned xb_ld(unsigned* p)              { return __hip_atomic_load(p, __ATOMIC_RELAXED, __HIP_MEMORY_SCOPE_AGENT); }
; __device__ __forceinline__ void xcd_barrier_complete(unsigned* bar, unsigned x, unsigned& nloc, unsigned& nx) {
;     const unsigned G = gridDim.x * gridDim.y * gridDim.z;
;     unsigned sum, cnt, mine, sp = 0u;
;     for (;;) {
;         sum = 0u; cnt = 0u; mine = 0u;
; #pragma unroll
;         for (unsigned j = 0; j < 16; ++j) { const unsigned c = xb_ld(&bar[XB_XCNT(j)]); sum += c; cnt += (c > 0u) ? 1u : 0u; mine = (j == x) ? c : mine; }
; __device__ __forceinline__ void xcd_barrier(const XcdBarrier& b) {
;     asm volatile("s_waitcnt vmcnt(0)" ::: "memory");
;     __syncthreads();
;     if (threadIdx.x == 0) {
;         unsigned* bar = b.bar;
;         __builtin_amdgcn_s_waitcnt(0);
;         unsigned nloc = b.st[0], nx = b.st[1];
;         if (nloc == 0u) { xcd_barrier_complete(bar, b.x, nloc, nx); b.st[0] = nloc; b.st[1] = nx; }
.LBB0_160:
	s_cmp_gt_i32 s31, 2
	s_cselect_b64 s[0:1], -1, 0
	s_and_b64 s[4:5], s[6:7], s[0:1]
	s_andn2_b64 vcc, exec, s[4:5]
	s_cbranch_vccnz .LBB0_210
	s_waitcnt vmcnt(0)
	v_cmp_eq_u32_e32 vcc, 0, v0
	s_waitcnt vmcnt(63) expcnt(7) lgkmcnt(15)
	s_barrier
	s_and_saveexec_b64 s[4:5], vcc
	s_cbranch_execz .LBB0_209
	v_mov_b32_e32 v1, s97
	buffer_wbl2 sc1
	s_waitcnt vmcnt(0) expcnt(0) lgkmcnt(0)
	ds_read_b32 v3, v1
	ds_read_b32 v1, v1 offset:4
	s_waitcnt lgkmcnt(1)
	v_cmp_ne_u32_e32 vcc, 0, v3
	s_cbranch_vccnz .LBB0_177
	v_readlane_b32 s6, v244, 0
	v_readlane_b32 s7, v244, 1
	s_load_dwordx2 s[12:13], s[6:7], 0x4
	s_add_u32 s6, s28, 0x4200
	s_addc_u32 s7, s29, 0
	s_add_u32 s10, s28, 0x4400
	s_addc_u32 s11, s29, 0
	s_waitcnt lgkmcnt(0)
	s_mul_i32 s3, s12, s33
	s_add_u32 s12, s28, 0x4500
	s_mul_i32 s3, s3, s13
	s_addc_u32 s13, s29, 0
	s_add_u32 s14, s28, 0x4600
	s_addc_u32 s15, s29, 0
	s_add_u32 s16, s28, 0x4700
	s_addc_u32 s17, s29, 0
	s_add_u32 s38, s28, 0x4800
	s_addc_u32 s39, s29, 0
	s_add_u32 s46, s28, 0x4900
	s_addc_u32 s47, s29, 0
	s_add_u32 s50, s28, 0x4a00
	s_addc_u32 s51, s29, 0
	s_add_u32 s62, s28, 0x4b00
	s_addc_u32 s63, s29, 0
	s_add_u32 s66, s28, 0x4c00
	s_addc_u32 s67, s29, 0
	s_add_u32 s76, s28, 0x4d00
	s_addc_u32 s77, s29, 0
	s_add_u32 s82, s28, 0x4e00
	s_addc_u32 s83, s29, 0
	s_add_u32 s84, s28, 0x4f00
	s_addc_u32 s85, s29, 0
	s_add_u32 s86, s28, 0x5000
	s_addc_u32 s87, s29, 0
	s_add_u32 s88, s28, 0x5100
	s_addc_u32 s89, s29, 0
	s_add_u32 s90, s28, 0x5200
	s_addc_u32 s91, s29, 0
	s_add_u32 s60, s28, 0x5300
	s_mov_b32 s53, s93
	s_addc_u32 s61, s29, 0
	s_mov_b32 s35, 1
	v_mov_b32_e32 v17, 0
	s_branch .LBB0_165

; __device__ __forceinline__ unsigned xb_ld(unsigned* p)              { return __hip_atomic_load(p, __ATOMIC_RELAXED, __HIP_MEMORY_SCOPE_AGENT); }
; __device__ __forceinline__ void xcd_barrier_complete(unsigned* bar, unsigned x, unsigned& nloc, unsigned& nx) {
;     const unsigned G = gridDim.x * gridDim.y * gridDim.z;
;     unsigned sum, cnt, mine, sp = 0u;
;     for (;;) {
;         sum = 0u; cnt = 0u; mine = 0u;
; #pragma unroll
;         for (unsigned j = 0; j < 16; ++j) { const unsigned c = xb_ld(&bar[XB_XCNT(j)]); sum += c; cnt += (c > 0u) ? 1u : 0u; mine = (j == x) ? c : mine; }
; __device__ __forceinline__ void xcd_barrier(const XcdBarrier& b) {
;     asm volatile("s_waitcnt vmcnt(0)" ::: "memory");
;     __syncthreads();
;     if (threadIdx.x == 0) {
;         unsigned* bar = b.bar;
;         __builtin_amdgcn_s_waitcnt(0);
;         unsigned nloc = b.st[0], nx = b.st[1];
;         if (nloc == 0u) { xcd_barrier_complete(bar, b.x, nloc, nx); b.st[0] = nloc; b.st[1] = nx; }
.LBB0_257:
	s_cmp_gt_i32 s31, 3
	s_cselect_b64 s[0:1], -1, 0
	s_and_b64 s[4:5], s[10:11], s[0:1]
	s_andn2_b64 vcc, exec, s[4:5]
	s_cbranch_vccnz .LBB0_307
	s_waitcnt vmcnt(0)
	v_cmp_eq_u32_e32 vcc, 0, v0
	s_waitcnt lgkmcnt(0)
	s_barrier
	s_and_saveexec_b64 s[4:5], vcc
	s_cbranch_execz .LBB0_306
	v_mov_b32_e32 v1, s97
	buffer_wbl2 sc1
	s_waitcnt vmcnt(0) expcnt(0) lgkmcnt(0)
	ds_read_b32 v3, v1
	ds_read_b32 v1, v1 offset:4
	s_waitcnt lgkmcnt(1)
	v_cmp_ne_u32_e32 vcc, 0, v3
	s_cbranch_vccnz .LBB0_274
	v_readlane_b32 s6, v244, 0
	v_readlane_b32 s7, v244, 1
	s_load_dwordx2 s[10:11], s[6:7], 0x4
	s_add_u32 s6, s28, 0x4200
	s_addc_u32 s7, s29, 0
	s_add_u32 s8, s28, 0x4400
	s_addc_u32 s9, s29, 0
	s_waitcnt lgkmcnt(0)
	s_mul_i32 s3, s10, s33
	s_add_u32 s10, s28, 0x4500
	s_mul_i32 s3, s3, s11
	s_addc_u32 s11, s29, 0
	s_add_u32 s12, s28, 0x4600
	s_addc_u32 s13, s29, 0
	s_add_u32 s14, s28, 0x4700
	s_addc_u32 s15, s29, 0
	s_add_u32 s16, s28, 0x4800
	s_addc_u32 s17, s29, 0
	s_add_u32 s18, s28, 0x4900
	s_addc_u32 s19, s29, 0
	s_add_u32 s46, s28, 0x4a00
	s_addc_u32 s47, s29, 0
	s_add_u32 s50, s28, 0x4b00
	s_addc_u32 s51, s29, 0
	s_add_u32 s62, s28, 0x4c00
	s_addc_u32 s63, s29, 0
	s_add_u32 s66, s28, 0x4d00
	s_addc_u32 s67, s29, 0
	s_add_u32 s76, s28, 0x4e00
	s_addc_u32 s77, s29, 0
	s_add_u32 s80, s28, 0x4f00
	s_addc_u32 s81, s29, 0
	s_add_u32 s82, s28, 0x5000
	s_addc_u32 s83, s29, 0
	s_add_u32 s84, s28, 0x5100
	s_addc_u32 s85, s29, 0
	s_add_u32 s86, s28, 0x5200
	s_addc_u32 s87, s29, 0
	s_add_u32 s60, s28, 0x5300
	s_addc_u32 s61, s29, 0
	s_mov_b32 s35, 1
	v_mov_b32_e32 v17, 0
	s_branch .LBB0_262

; __device__ __forceinline__ unsigned xb_ld(unsigned* p)              { return __hip_atomic_load(p, __ATOMIC_RELAXED, __HIP_MEMORY_SCOPE_AGENT); }
; __device__ __forceinline__ void xcd_barrier_complete(unsigned* bar, unsigned x, unsigned& nloc, unsigned& nx) {
;     const unsigned G = gridDim.x * gridDim.y * gridDim.z;
;     unsigned sum, cnt, mine, sp = 0u;
;     for (;;) {
;         sum = 0u; cnt = 0u; mine = 0u;
; #pragma unroll
;         for (unsigned j = 0; j < 16; ++j) { const unsigned c = xb_ld(&bar[XB_XCNT(j)]); sum += c; cnt += (c > 0u) ? 1u : 0u; mine = (j == x) ? c : mine; }
; __device__ __forceinline__ void xcd_barrier(const XcdBarrier& b) {
;     asm volatile("s_waitcnt vmcnt(0)" ::: "memory");
;     __syncthreads();
;     if (threadIdx.x == 0) {
;         unsigned* bar = b.bar;
;         __builtin_amdgcn_s_waitcnt(0);
;         unsigned nloc = b.st[0], nx = b.st[1];
;         if (nloc == 0u) { xcd_barrier_complete(bar, b.x, nloc, nx); b.st[0] = nloc; b.st[1] = nx; }
.LBB0_335:
	s_cmp_gt_i32 s31, 4
	s_cselect_b64 s[0:1], -1, 0
	s_and_b64 s[4:5], s[12:13], s[0:1]
	s_andn2_b64 vcc, exec, s[4:5]
	s_cbranch_vccnz .LBB0_385
	s_waitcnt vmcnt(0)
	v_cmp_eq_u32_e32 vcc, 0, v0
	s_waitcnt lgkmcnt(0)
	s_barrier
	s_and_saveexec_b64 s[4:5], vcc
	s_cbranch_execz .LBB0_384
	v_mov_b32_e32 v1, s97
	buffer_wbl2 sc1
	s_waitcnt vmcnt(0) expcnt(0) lgkmcnt(0)
	ds_read_b32 v3, v1
	ds_read_b32 v1, v1 offset:4
	s_waitcnt lgkmcnt(1)
	v_cmp_ne_u32_e32 vcc, 0, v3
	s_cbranch_vccnz .LBB0_352
	v_readlane_b32 s6, v244, 0
	v_readlane_b32 s7, v244, 1
	s_load_dwordx2 s[12:13], s[6:7], 0x4
	s_add_u32 s6, s28, 0x4200
	s_addc_u32 s7, s29, 0
	s_add_u32 s8, s28, 0x4400
	s_addc_u32 s9, s29, 0
	s_waitcnt lgkmcnt(0)
	s_mul_i32 s3, s12, s33
	s_add_u32 s12, s28, 0x4500
	s_mul_i32 s3, s3, s13
	s_addc_u32 s13, s29, 0
	s_add_u32 s14, s28, 0x4600
	s_addc_u32 s15, s29, 0
	s_add_u32 s16, s28, 0x4700
	s_addc_u32 s17, s29, 0
	s_add_u32 s18, s28, 0x4800
	s_addc_u32 s19, s29, 0
	s_add_u32 s46, s28, 0x4900
	s_addc_u32 s47, s29, 0
	s_add_u32 s50, s28, 0x4a00
	s_addc_u32 s51, s29, 0
	s_add_u32 s62, s28, 0x4b00
	s_addc_u32 s63, s29, 0
	s_add_u32 s66, s28, 0x4c00
	s_addc_u32 s67, s29, 0
	s_add_u32 s76, s28, 0x4d00
	s_addc_u32 s77, s29, 0
	s_add_u32 s78, s28, 0x4e00
	s_addc_u32 s79, s29, 0
	s_add_u32 s80, s28, 0x4f00
	s_addc_u32 s81, s29, 0
	s_add_u32 s82, s28, 0x5000
	s_addc_u32 s83, s29, 0
	s_add_u32 s84, s28, 0x5100
	s_addc_u32 s85, s29, 0
	s_add_u32 s86, s28, 0x5200
	s_addc_u32 s87, s29, 0
	s_add_u32 s60, s28, 0x5300
	s_addc_u32 s61, s29, 0
	s_mov_b32 s35, 1
	v_mov_b32_e32 v17, 0
	s_branch .LBB0_340

; __device__ __forceinline__ unsigned xb_ld(unsigned* p)              { return __hip_atomic_load(p, __ATOMIC_RELAXED, __HIP_MEMORY_SCOPE_AGENT); }
; __device__ __forceinline__ void xcd_barrier_complete(unsigned* bar, unsigned x, unsigned& nloc, unsigned& nx) {
;     const unsigned G = gridDim.x * gridDim.y * gridDim.z;
;     unsigned sum, cnt, mine, sp = 0u;
;     for (;;) {
;         sum = 0u; cnt = 0u; mine = 0u;
; #pragma unroll
;         for (unsigned j = 0; j < 16; ++j) { const unsigned c = xb_ld(&bar[XB_XCNT(j)]); sum += c; cnt += (c > 0u) ? 1u : 0u; mine = (j == x) ? c : mine; }
; __device__ __forceinline__ void xcd_barrier(const XcdBarrier& b) {
;     asm volatile("s_waitcnt vmcnt(0)" ::: "memory");
;     __syncthreads();
;     if (threadIdx.x == 0) {
;         unsigned* bar = b.bar;
;         __builtin_amdgcn_s_waitcnt(0);
;         unsigned nloc = b.st[0], nx = b.st[1];
;         if (nloc == 0u) { xcd_barrier_complete(bar, b.x, nloc, nx); b.st[0] = nloc; b.st[1] = nx; }
.LBB0_408:
	s_cmp_gt_i32 s31, 5
	s_cselect_b64 s[0:1], -1, 0
	s_and_b64 s[4:5], s[84:85], s[0:1]
	s_andn2_b64 vcc, exec, s[4:5]
	s_cbranch_vccnz .LBB0_458
	s_waitcnt vmcnt(0)
	v_cmp_eq_u32_e32 vcc, 0, v0
	s_waitcnt lgkmcnt(0)
	s_barrier
	s_and_saveexec_b64 s[4:5], vcc
	s_cbranch_execz .LBB0_457
	v_mov_b32_e32 v1, s97
	buffer_wbl2 sc1
	s_waitcnt vmcnt(0) expcnt(0) lgkmcnt(0)
	ds_read_b32 v3, v1
	ds_read_b32 v1, v1 offset:4
	s_waitcnt lgkmcnt(1)
	v_cmp_ne_u32_e32 vcc, 0, v3
	s_cbranch_vccnz .LBB0_425
	v_readlane_b32 s6, v244, 0
	v_readlane_b32 s7, v244, 1
	s_load_dwordx2 s[10:11], s[6:7], 0x4
	s_add_u32 s6, s28, 0x4200
	s_addc_u32 s7, s29, 0
	s_add_u32 s8, s28, 0x4400
	s_addc_u32 s9, s29, 0
	s_waitcnt lgkmcnt(0)
	s_mul_i32 s3, s10, s33
	s_add_u32 s10, s28, 0x4500
	s_mul_i32 s3, s3, s11
	s_addc_u32 s11, s29, 0
	s_add_u32 s12, s28, 0x4600
	s_addc_u32 s13, s29, 0
	s_add_u32 s14, s28, 0x4700
	s_addc_u32 s15, s29, 0
	s_add_u32 s16, s28, 0x4800
	s_addc_u32 s17, s29, 0
	s_add_u32 s18, s28, 0x4900
	s_addc_u32 s19, s29, 0
	s_add_u32 s22, s28, 0x4a00
	s_addc_u32 s23, s29, 0
	s_add_u32 s36, s28, 0x4b00
	s_addc_u32 s37, s29, 0
	s_add_u32 s40, s28, 0x4c00
	s_addc_u32 s41, s29, 0
	s_add_u32 s42, s28, 0x4d00
	s_addc_u32 s43, s29, 0
	s_add_u32 s62, s28, 0x4e00
	s_addc_u32 s63, s29, 0
	s_add_u32 s66, s28, 0x4f00
	s_addc_u32 s67, s29, 0
	s_add_u32 s76, s28, 0x5000
	s_addc_u32 s77, s29, 0
	s_add_u32 s84, s28, 0x5100
	s_addc_u32 s85, s29, 0
	s_add_u32 s86, s28, 0x5200
	s_addc_u32 s87, s29, 0
	s_add_u32 s60, s28, 0x5300
	s_addc_u32 s61, s29, 0
	s_mov_b32 s35, 1
	v_mov_b32_e32 v17, 0
	s_branch .LBB0_413

; __device__ __forceinline__ unsigned xb_ld(unsigned* p)              { return __hip_atomic_load(p, __ATOMIC_RELAXED, __HIP_MEMORY_SCOPE_AGENT); }
; __device__ __forceinline__ void xcd_barrier_complete(unsigned* bar, unsigned x, unsigned& nloc, unsigned& nx) {
;     const unsigned G = gridDim.x * gridDim.y * gridDim.z;
;     unsigned sum, cnt, mine, sp = 0u;
;     for (;;) {
;         sum = 0u; cnt = 0u; mine = 0u;
; #pragma unroll
;         for (unsigned j = 0; j < 16; ++j) { const unsigned c = xb_ld(&bar[XB_XCNT(j)]); sum += c; cnt += (c > 0u) ? 1u : 0u; mine = (j == x) ? c : mine; }
; __device__ __forceinline__ void xcd_barrier(const XcdBarrier& b) {
;     asm volatile("s_waitcnt vmcnt(0)" ::: "memory");
;     __syncthreads();
;     if (threadIdx.x == 0) {
;         unsigned* bar = b.bar;
;         __builtin_amdgcn_s_waitcnt(0);
;         unsigned nloc = b.st[0], nx = b.st[1];
;         if (nloc == 0u) { xcd_barrier_complete(bar, b.x, nloc, nx); b.st[0] = nloc; b.st[1] = nx; }
.LBB0_497:
	s_cmp_gt_i32 s31, 6
	s_cselect_b64 s[0:1], -1, 0
	s_and_b64 s[4:5], s[4:5], s[0:1]
	v_readlane_b32 s78, v244, 21
	s_andn2_b64 vcc, exec, s[4:5]
	v_readlane_b32 s79, v244, 22
	s_cbranch_vccnz .LBB0_547
	s_waitcnt vmcnt(0)
	v_cmp_eq_u32_e32 vcc, 0, v0
	s_waitcnt lgkmcnt(0)
	s_barrier
	s_and_saveexec_b64 s[4:5], vcc
	s_cbranch_execz .LBB0_546
	v_mov_b32_e32 v1, s97
	buffer_wbl2 sc1
	s_waitcnt vmcnt(0) expcnt(0) lgkmcnt(0)
	ds_read_b32 v3, v1
	ds_read_b32 v1, v1 offset:4
	s_waitcnt lgkmcnt(1)
	v_cmp_ne_u32_e32 vcc, 0, v3
	s_cbranch_vccnz .LBB0_514
	v_readlane_b32 s6, v244, 0
	v_readlane_b32 s7, v244, 1
	s_load_dwordx2 s[10:11], s[6:7], 0x4
	s_add_u32 s6, s28, 0x4200
	s_addc_u32 s7, s29, 0
	s_add_u32 s8, s28, 0x4400
	s_addc_u32 s9, s29, 0
	s_waitcnt lgkmcnt(0)
	s_mul_i32 s3, s10, s33
	s_add_u32 s10, s28, 0x4500
	s_mul_i32 s3, s3, s11
	s_addc_u32 s11, s29, 0
	s_add_u32 s12, s28, 0x4600
	s_addc_u32 s13, s29, 0
	s_add_u32 s14, s28, 0x4700
	s_addc_u32 s15, s29, 0
	s_add_u32 s16, s28, 0x4800
	s_addc_u32 s17, s29, 0
	s_add_u32 s18, s28, 0x4900
	s_addc_u32 s19, s29, 0
	s_add_u32 s22, s28, 0x4a00
	s_addc_u32 s23, s29, 0
	s_add_u32 s36, s28, 0x4b00
	s_addc_u32 s37, s29, 0
	s_add_u32 s40, s28, 0x4c00
	s_addc_u32 s41, s29, 0
	s_add_u32 s42, s28, 0x4d00
	s_addc_u32 s43, s29, 0
	s_add_u32 s46, s28, 0x4e00
	s_addc_u32 s47, s29, 0
	s_add_u32 s50, s28, 0x4f00
	s_addc_u32 s51, s29, 0
	s_add_u32 s54, s28, 0x5000
	s_addc_u32 s55, s29, 0
	s_add_u32 s56, s28, 0x5100
	s_addc_u32 s57, s29, 0
	s_add_u32 s62, s28, 0x5200
	s_addc_u32 s63, s29, 0
	s_add_u32 s60, s28, 0x5300
	s_addc_u32 s61, s29, 0
	s_mov_b32 s35, 1
	v_mov_b32_e32 v17, 0
	s_branch .LBB0_502

; __device__ __forceinline__ unsigned xb_ld(unsigned* p)              { return __hip_atomic_load(p, __ATOMIC_RELAXED, __HIP_MEMORY_SCOPE_AGENT); }
; __device__ __forceinline__ void xcd_barrier_complete(unsigned* bar, unsigned x, unsigned& nloc, unsigned& nx) {
;     const unsigned G = gridDim.x * gridDim.y * gridDim.z;
;     unsigned sum, cnt, mine, sp = 0u;
;     for (;;) {
;         sum = 0u; cnt = 0u; mine = 0u;
; #pragma unroll
;         for (unsigned j = 0; j < 16; ++j) { const unsigned c = xb_ld(&bar[XB_XCNT(j)]); sum += c; cnt += (c > 0u) ? 1u : 0u; mine = (j == x) ? c : mine; }
; __device__ __forceinline__ void xcd_barrier(const XcdBarrier& b) {
;     asm volatile("s_waitcnt vmcnt(0)" ::: "memory");
;     __syncthreads();
;     if (threadIdx.x == 0) {
;         unsigned* bar = b.bar;
;         __builtin_amdgcn_s_waitcnt(0);
;         unsigned nloc = b.st[0], nx = b.st[1];
;         if (nloc == 0u) { xcd_barrier_complete(bar, b.x, nloc, nx); b.st[0] = nloc; b.st[1] = nx; }
.LBB0_551:
	s_cmp_gt_i32 s31, 7
	v_readlane_b32 s80, v244, 2
	s_cselect_b64 s[0:1], -1, 0
	v_readlane_b32 s82, v244, 4
	v_readlane_b32 s83, v244, 5
	s_and_b64 s[4:5], s[4:5], s[0:1]
	v_readlane_b32 s82, v244, 17
	s_andn2_b64 vcc, exec, s[4:5]
	v_readlane_b32 s81, v244, 3
	v_readlane_b32 s86, v244, 8
	v_readlane_b32 s87, v244, 9
	v_readlane_b32 s83, v244, 18
	v_readlane_b32 s84, v244, 6
	v_readlane_b32 s85, v244, 7
	s_cbranch_vccnz .LBB0_601
	s_waitcnt vmcnt(0)
	v_cmp_eq_u32_e32 vcc, 0, v0
	s_waitcnt lgkmcnt(0)
	s_barrier
	s_and_saveexec_b64 s[4:5], vcc
	s_cbranch_execz .LBB0_600
	v_mov_b32_e32 v1, s97
	buffer_wbl2 sc1
	s_waitcnt vmcnt(0) expcnt(0) lgkmcnt(0)
	ds_read_b32 v3, v1
	ds_read_b32 v1, v1 offset:4
	s_waitcnt lgkmcnt(1)
	v_cmp_ne_u32_e32 vcc, 0, v3
	s_cbranch_vccnz .LBB0_568
	v_readlane_b32 s6, v244, 0
	v_readlane_b32 s7, v244, 1
	s_load_dwordx2 s[10:11], s[6:7], 0x4
	s_add_u32 s6, s28, 0x4200
	s_addc_u32 s7, s29, 0
	s_add_u32 s8, s28, 0x4400
	s_addc_u32 s9, s29, 0
	s_waitcnt lgkmcnt(0)
	s_mul_i32 s52, s10, s33
	s_add_u32 s10, s28, 0x4500
	s_mul_i32 s52, s52, s11
	s_addc_u32 s11, s29, 0
	s_add_u32 s12, s28, 0x4600
	s_addc_u32 s13, s29, 0
	s_add_u32 s14, s28, 0x4700
	s_addc_u32 s15, s29, 0
	s_add_u32 s16, s28, 0x4800
	s_addc_u32 s17, s29, 0
	s_add_u32 s18, s28, 0x4900
	s_addc_u32 s19, s29, 0
	s_add_u32 s22, s28, 0x4a00
	s_addc_u32 s23, s29, 0
	s_add_u32 s36, s28, 0x4b00
	s_addc_u32 s37, s29, 0
	s_add_u32 s40, s28, 0x4c00
	s_addc_u32 s41, s29, 0
	s_add_u32 s42, s28, 0x4d00
	s_addc_u32 s43, s29, 0
	s_add_u32 s44, s28, 0x4e00
	s_addc_u32 s45, s29, 0
	s_add_u32 s46, s28, 0x4f00
	s_addc_u32 s47, s29, 0
	s_add_u32 s50, s28, 0x5000
	s_addc_u32 s51, s29, 0
	s_add_u32 s54, s28, 0x5100
	s_addc_u32 s55, s29, 0
	s_add_u32 s56, s28, 0x5200
	s_addc_u32 s57, s29, 0
	s_add_u32 s60, s28, 0x5300
	s_addc_u32 s61, s29, 0
	s_mov_b32 s53, 1
	v_mov_b32_e32 v17, 0
	s_branch .LBB0_556

; __device__ __forceinline__ unsigned xb_ld(unsigned* p)              { return __hip_atomic_load(p, __ATOMIC_RELAXED, __HIP_MEMORY_SCOPE_AGENT); }
; __device__ __forceinline__ void xcd_barrier_complete(unsigned* bar, unsigned x, unsigned& nloc, unsigned& nx) {
;     const unsigned G = gridDim.x * gridDim.y * gridDim.z;
;     unsigned sum, cnt, mine, sp = 0u;
;     for (;;) {
;         sum = 0u; cnt = 0u; mine = 0u;
; #pragma unroll
;         for (unsigned j = 0; j < 16; ++j) { const unsigned c = xb_ld(&bar[XB_XCNT(j)]); sum += c; cnt += (c > 0u) ? 1u : 0u; mine = (j == x) ? c : mine; }
; __device__ __forceinline__ void xcd_barrier(const XcdBarrier& b) {
;     asm volatile("s_waitcnt vmcnt(0)" ::: "memory");
;     __syncthreads();
;     if (threadIdx.x == 0) {
;         unsigned* bar = b.bar;
;         __builtin_amdgcn_s_waitcnt(0);
;         unsigned nloc = b.st[0], nx = b.st[1];
;         if (nloc == 0u) { xcd_barrier_complete(bar, b.x, nloc, nx); b.st[0] = nloc; b.st[1] = nx; }
.LBB0_628:
	s_cmp_gt_i32 s31, 8
	s_cselect_b64 s[0:1], -1, 0
	s_and_b64 s[4:5], s[4:5], s[0:1]
	s_andn2_b64 vcc, exec, s[4:5]
	s_cbranch_vccnz .LBB0_678
	s_waitcnt vmcnt(0)
	v_cmp_eq_u32_e32 vcc, 0, v0
	s_waitcnt lgkmcnt(0)
	s_barrier
	s_and_saveexec_b64 s[4:5], vcc
	s_cbranch_execz .LBB0_677
	v_mov_b32_e32 v1, s97
	buffer_wbl2 sc1
	s_waitcnt vmcnt(0) expcnt(0) lgkmcnt(0)
	ds_read_b32 v3, v1
	ds_read_b32 v1, v1 offset:4
	s_waitcnt lgkmcnt(1)
	v_cmp_ne_u32_e32 vcc, 0, v3
	s_cbranch_vccnz .LBB0_645
	v_readlane_b32 s8, v244, 0
	v_readlane_b32 s9, v244, 1
	s_load_dwordx2 s[12:13], s[8:9], 0x4
	s_add_u32 s8, s28, 0x4200
	s_addc_u32 s9, s29, 0
	s_add_u32 s10, s28, 0x4400
	s_addc_u32 s11, s29, 0
	s_waitcnt lgkmcnt(0)
	s_mul_i32 s3, s12, s33
	s_add_u32 s12, s28, 0x4500
	s_mul_i32 s3, s3, s13
	s_addc_u32 s13, s29, 0
	s_add_u32 s14, s28, 0x4600
	s_addc_u32 s15, s29, 0
	s_add_u32 s16, s28, 0x4700
	s_addc_u32 s17, s29, 0
	s_add_u32 s18, s28, 0x4800
	s_addc_u32 s19, s29, 0
	s_add_u32 s22, s28, 0x4900
	s_addc_u32 s23, s29, 0
	s_add_u32 s36, s28, 0x4a00
	s_addc_u32 s37, s29, 0
	s_add_u32 s40, s28, 0x4b00
	s_addc_u32 s41, s29, 0
	s_add_u32 s42, s28, 0x4c00
	s_addc_u32 s43, s29, 0
	s_add_u32 s44, s28, 0x4d00
	s_addc_u32 s45, s29, 0
	s_add_u32 s46, s28, 0x4e00
	s_addc_u32 s47, s29, 0
	s_add_u32 s48, s28, 0x4f00
	s_addc_u32 s49, s29, 0
	s_add_u32 s50, s28, 0x5000
	s_addc_u32 s51, s29, 0
	s_add_u32 s54, s28, 0x5100
	s_addc_u32 s55, s29, 0
	s_add_u32 s56, s28, 0x5200
	s_addc_u32 s57, s29, 0
	s_add_u32 s60, s28, 0x5300
	s_addc_u32 s61, s29, 0
	s_mov_b32 s35, 1
	v_mov_b32_e32 v17, 0
	s_branch .LBB0_633

; __device__ __forceinline__ unsigned xb_ld(unsigned* p)              { return __hip_atomic_load(p, __ATOMIC_RELAXED, __HIP_MEMORY_SCOPE_AGENT); }
; __device__ __forceinline__ void xcd_barrier_complete(unsigned* bar, unsigned x, unsigned& nloc, unsigned& nx) {
;     const unsigned G = gridDim.x * gridDim.y * gridDim.z;
;     unsigned sum, cnt, mine, sp = 0u;
;     for (;;) {
;         sum = 0u; cnt = 0u; mine = 0u;
; #pragma unroll
;         for (unsigned j = 0; j < 16; ++j) { const unsigned c = xb_ld(&bar[XB_XCNT(j)]); sum += c; cnt += (c > 0u) ? 1u : 0u; mine = (j == x) ? c : mine; }
; __device__ __forceinline__ void xcd_barrier(const XcdBarrier& b) {
;     asm volatile("s_waitcnt vmcnt(0)" ::: "memory");
;     __syncthreads();
;     if (threadIdx.x == 0) {
;         unsigned* bar = b.bar;
;         __builtin_amdgcn_s_waitcnt(0);
;         unsigned nloc = b.st[0], nx = b.st[1];
;         if (nloc == 0u) { xcd_barrier_complete(bar, b.x, nloc, nx); b.st[0] = nloc; b.st[1] = nx; }
.LBB0_721:
	s_cmp_gt_i32 s31, 9
	s_cselect_b64 s[0:1], -1, 0
	s_and_b64 s[4:5], s[8:9], s[0:1]
	v_readlane_b32 s80, v244, 19
	s_andn2_b64 vcc, exec, s[4:5]
	v_readlane_b32 s81, v244, 20
	s_cbranch_vccnz .LBB0_771
	s_waitcnt vmcnt(0)
	v_cmp_eq_u32_e32 vcc, 0, v0
	s_waitcnt lgkmcnt(0)
	s_barrier
	s_and_saveexec_b64 s[4:5], vcc
	s_cbranch_execz .LBB0_770
	v_mov_b32_e32 v1, s97
	buffer_wbl2 sc1
	s_waitcnt vmcnt(0) expcnt(0) lgkmcnt(0)
	ds_read_b32 v3, v1
	ds_read_b32 v1, v1 offset:4
	s_waitcnt lgkmcnt(1)
	v_cmp_ne_u32_e32 vcc, 0, v3
	s_cbranch_vccnz .LBB0_738
	v_readlane_b32 s6, v244, 0
	v_readlane_b32 s7, v244, 1
	s_load_dwordx2 s[10:11], s[6:7], 0x4
	s_add_u32 s6, s28, 0x4200
	s_addc_u32 s7, s29, 0
	s_add_u32 s8, s28, 0x4400
	s_addc_u32 s9, s29, 0
	s_waitcnt lgkmcnt(0)
	s_mul_i32 s3, s10, s33
	s_add_u32 s10, s28, 0x4500
	s_mul_i32 s3, s3, s11
	s_addc_u32 s11, s29, 0
	s_add_u32 s12, s28, 0x4600
	s_addc_u32 s13, s29, 0
	s_add_u32 s14, s28, 0x4700
	s_addc_u32 s15, s29, 0
	s_add_u32 s16, s28, 0x4800
	s_addc_u32 s17, s29, 0
	s_add_u32 s18, s28, 0x4900
	s_addc_u32 s19, s29, 0
	s_add_u32 s22, s28, 0x4a00
	s_addc_u32 s23, s29, 0
	s_add_u32 s36, s28, 0x4b00
	s_addc_u32 s37, s29, 0
	s_add_u32 s40, s28, 0x4c00
	s_addc_u32 s41, s29, 0
	s_add_u32 s42, s28, 0x4d00
	s_addc_u32 s43, s29, 0
	s_add_u32 s44, s28, 0x4e00
	s_addc_u32 s45, s29, 0
	s_add_u32 s46, s28, 0x4f00
	s_addc_u32 s47, s29, 0
	s_add_u32 s48, s28, 0x5000
	s_addc_u32 s49, s29, 0
	s_add_u32 s50, s28, 0x5100
	s_addc_u32 s51, s29, 0
	s_add_u32 s52, s28, 0x5200
	s_addc_u32 s53, s29, 0
	s_add_u32 s54, s28, 0x5300
	s_addc_u32 s55, s29, 0
	s_mov_b32 s35, 1
	v_mov_b32_e32 v17, 0
	s_branch .LBB0_726

; __device__ __forceinline__ unsigned xb_ld(unsigned* p)              { return __hip_atomic_load(p, __ATOMIC_RELAXED, __HIP_MEMORY_SCOPE_AGENT); }
; __device__ __forceinline__ void xcd_barrier_complete(unsigned* bar, unsigned x, unsigned& nloc, unsigned& nx) {
;     const unsigned G = gridDim.x * gridDim.y * gridDim.z;
;     unsigned sum, cnt, mine, sp = 0u;
;     for (;;) {
;         sum = 0u; cnt = 0u; mine = 0u;
; #pragma unroll
;         for (unsigned j = 0; j < 16; ++j) { const unsigned c = xb_ld(&bar[XB_XCNT(j)]); sum += c; cnt += (c > 0u) ? 1u : 0u; mine = (j == x) ? c : mine; }
; __device__ __forceinline__ void xcd_barrier(const XcdBarrier& b) {
;     asm volatile("s_waitcnt vmcnt(0)" ::: "memory");
;     __syncthreads();
;     if (threadIdx.x == 0) {
;         unsigned* bar = b.bar;
;         __builtin_amdgcn_s_waitcnt(0);
;         unsigned nloc = b.st[0], nx = b.st[1];
;         if (nloc == 0u) { xcd_barrier_complete(bar, b.x, nloc, nx); b.st[0] = nloc; b.st[1] = nx; }
.LBB0_801:
	s_cmp_gt_i32 s31, 10
	s_cselect_b64 s[0:1], -1, 0
	s_and_b64 s[4:5], s[10:11], s[0:1]
	s_andn2_b64 vcc, exec, s[4:5]
	s_cbranch_vccnz .LBB0_851
	s_waitcnt vmcnt(0)
	v_cmp_eq_u32_e32 vcc, 0, v0
	s_waitcnt lgkmcnt(0)
	s_barrier
	s_and_saveexec_b64 s[4:5], vcc
	s_cbranch_execz .LBB0_850
	v_mov_b32_e32 v1, s97
	buffer_wbl2 sc1
	s_waitcnt vmcnt(0) expcnt(0) lgkmcnt(0)
	ds_read_b32 v3, v1
	ds_read_b32 v1, v1 offset:4
	s_waitcnt lgkmcnt(1)
	v_cmp_ne_u32_e32 vcc, 0, v3
	s_cbranch_vccnz .LBB0_818
	v_readlane_b32 s6, v244, 0
	v_readlane_b32 s7, v244, 1
	s_load_dwordx2 s[10:11], s[6:7], 0x4
	s_add_u32 s6, s28, 0x4200
	s_addc_u32 s7, s29, 0
	s_add_u32 s8, s28, 0x4400
	s_addc_u32 s9, s29, 0
	s_waitcnt lgkmcnt(0)
	s_mul_i32 s3, s10, s33
	s_add_u32 s10, s28, 0x4500
	s_mul_i32 s3, s3, s11
	s_addc_u32 s11, s29, 0
	s_add_u32 s12, s28, 0x4600
	s_addc_u32 s13, s29, 0
	s_add_u32 s14, s28, 0x4700
	s_addc_u32 s15, s29, 0
	s_add_u32 s16, s28, 0x4800
	s_addc_u32 s17, s29, 0
	s_add_u32 s18, s28, 0x4900
	s_addc_u32 s19, s29, 0
	s_add_u32 s22, s28, 0x4a00
	s_addc_u32 s23, s29, 0
	s_add_u32 s36, s28, 0x4b00
	s_addc_u32 s37, s29, 0
	s_add_u32 s38, s28, 0x4c00
	s_addc_u32 s39, s29, 0
	s_add_u32 s40, s28, 0x4d00
	s_addc_u32 s41, s29, 0
	s_add_u32 s42, s28, 0x4e00
	s_addc_u32 s43, s29, 0
	s_add_u32 s44, s28, 0x4f00
	s_addc_u32 s45, s29, 0
	s_add_u32 s46, s28, 0x5000
	s_addc_u32 s47, s29, 0
	s_add_u32 s48, s28, 0x5100
	s_addc_u32 s49, s29, 0
	s_add_u32 s50, s28, 0x5200
	s_addc_u32 s51, s29, 0
	s_add_u32 s52, s28, 0x5300
	s_addc_u32 s53, s29, 0
	s_mov_b32 s35, 1
	v_mov_b32_e32 v17, 0
	s_branch .LBB0_806

; __device__ __forceinline__ unsigned xb_ld(unsigned* p)              { return __hip_atomic_load(p, __ATOMIC_RELAXED, __HIP_MEMORY_SCOPE_AGENT); }
; __device__ __forceinline__ void xcd_barrier_complete(unsigned* bar, unsigned x, unsigned& nloc, unsigned& nx) {
;     const unsigned G = gridDim.x * gridDim.y * gridDim.z;
;     unsigned sum, cnt, mine, sp = 0u;
;     for (;;) {
;         sum = 0u; cnt = 0u; mine = 0u;
; #pragma unroll
;         for (unsigned j = 0; j < 16; ++j) { const unsigned c = xb_ld(&bar[XB_XCNT(j)]); sum += c; cnt += (c > 0u) ? 1u : 0u; mine = (j == x) ? c : mine; }
; __device__ __forceinline__ void xcd_barrier(const XcdBarrier& b) {
;     asm volatile("s_waitcnt vmcnt(0)" ::: "memory");
;     __syncthreads();
;     if (threadIdx.x == 0) {
;         unsigned* bar = b.bar;
;         __builtin_amdgcn_s_waitcnt(0);
;         unsigned nloc = b.st[0], nx = b.st[1];
;         if (nloc == 0u) { xcd_barrier_complete(bar, b.x, nloc, nx); b.st[0] = nloc; b.st[1] = nx; }
.LBB0_880:
	s_cmp_gt_i32 s31, 11
	s_cselect_b64 s[0:1], -1, 0
	s_and_b64 s[2:3], s[6:7], s[0:1]
	s_andn2_b64 vcc, exec, s[2:3]
	s_cbranch_vccnz .LBB0_930
	s_waitcnt vmcnt(0)
	v_cmp_eq_u32_e32 vcc, 0, v0
	s_waitcnt lgkmcnt(0)
	s_barrier
	s_and_saveexec_b64 s[2:3], vcc
	s_cbranch_execz .LBB0_929
	v_mov_b32_e32 v0, s97
	buffer_wbl2 sc1
	s_waitcnt vmcnt(0) expcnt(0) lgkmcnt(0)
	ds_read_b32 v2, v0
	ds_read_b32 v0, v0 offset:4
	s_waitcnt lgkmcnt(1)
	v_cmp_ne_u32_e32 vcc, 0, v2
	s_cbranch_vccnz .LBB0_897
	v_readlane_b32 s4, v244, 0
	v_readlane_b32 s5, v244, 1
	s_load_dwordx2 s[8:9], s[4:5], 0x4
	s_add_u32 s4, s28, 0x4200
	s_addc_u32 s5, s29, 0
	s_add_u32 s6, s28, 0x4400
	s_addc_u32 s7, s29, 0
	s_waitcnt lgkmcnt(0)
	s_mul_i32 s31, s8, s33
	s_add_u32 s8, s28, 0x4500
	s_mul_i32 s31, s31, s9
	s_addc_u32 s9, s29, 0
	s_add_u32 s10, s28, 0x4600
	s_addc_u32 s11, s29, 0
	s_add_u32 s12, s28, 0x4700
	s_addc_u32 s13, s29, 0
	s_add_u32 s14, s28, 0x4800
	s_addc_u32 s15, s29, 0
	s_add_u32 s16, s28, 0x4900
	s_addc_u32 s17, s29, 0
	s_add_u32 s18, s28, 0x4a00
	s_addc_u32 s19, s29, 0
	s_add_u32 s20, s28, 0x4b00
	s_addc_u32 s21, s29, 0
	s_add_u32 s22, s28, 0x4c00
	s_addc_u32 s23, s29, 0
	s_add_u32 s36, s28, 0x4d00
	s_addc_u32 s37, s29, 0
	s_add_u32 s38, s28, 0x4e00
	s_addc_u32 s39, s29, 0
	s_add_u32 s40, s28, 0x4f00
	s_addc_u32 s41, s29, 0
	s_add_u32 s42, s28, 0x5000
	s_addc_u32 s43, s29, 0
	s_add_u32 s44, s28, 0x5100
	s_addc_u32 s45, s29, 0
	s_add_u32 s46, s28, 0x5200
	s_addc_u32 s47, s29, 0
	s_add_u32 s48, s28, 0x5300
	s_addc_u32 s49, s29, 0
	s_mov_b32 s35, 1
	v_mov_b32_e32 v16, 0
	s_branch .LBB0_885
